# hyconv: next tile's cur row prefetched behind the current tile's last load wait
# speedup vs baseline: 1.0913x; 1.0050x over previous
; DI void phase_hyconv(const Ctx& c) {
;     ...
;   for (int it = blockIdx.x; it < (T / 64) * 24; it += gridDim.x) {
;     const int tt = it % (T / 64), ct = it / (T / 64);
;     const int t0 = tt * 64, c0 = ct * 64;
;     {
;       const int tr = tid >> 3, cs = (tid & 7) * 8;
;       const int tok = t0 + tr, n = tok & (L - 1);
;       float cur[8], prv[8], nxt[8];
;       unpack8(*(const uint4*)(P + (size_t)tok * 1536 + c0 + cs), cur);
.LBB0_267:
	s_or_b64 exec, exec, s[0:1]
	v_readlane_b32 s0, v228, 8
	v_readlane_b32 s1, v228, 9
	s_andn2_b64 vcc, exec, s[0:1]
	s_mov_b32 s0, s20
	s_mul_i32 s10, s20, 0x4800
	v_mov_b32_e32 v0, v186
	v_writelane_b32 v226, s0, 23
	s_barrier
	s_nop 0
	v_writelane_b32 v226, s1, 24
	s_cbranch_vccnz .LBB0_275
	v_readlane_b32 s40, v229, 38
	v_readlane_b32 s54, v229, 52
	v_readlane_b32 s41, v229, 39
	v_readlane_b32 s42, v229, 40
	v_readlane_b32 s43, v229, 41
	v_readlane_b32 s44, v229, 42
	v_readlane_b32 s45, v229, 43
	v_readlane_b32 s46, v229, 44
	v_readlane_b32 s47, v229, 45
	v_readlane_b32 s48, v229, 46
	v_readlane_b32 s49, v229, 47
	v_readlane_b32 s50, v229, 48
	v_readlane_b32 s51, v229, 49
	v_readlane_b32 s52, v229, 50
	v_readlane_b32 s53, v229, 51
	v_readlane_b32 s55, v229, 53
	s_add_u32 s0, s54, s10
	v_ashrrev_i32_e32 v7, 3, v0
	v_lshlrev_b32_e32 v0, 3, v0
	s_addc_u32 s1, s55, 0
	v_readlane_b32 s40, v229, 4
	v_and_b32_e32 v6, 56, v0
	s_movk_i32 s6, 0x90
	v_readlane_b32 s41, v229, 5
	v_mul_lo_u32 v0, v7, s6
	v_lshlrev_b32_e32 v2, 1, v6
	s_movk_i32 s6, 0x50
	s_mul_i32 s4, s20, 0x1800
	s_mov_b64 s[16:17], s[40:41]
	v_add3_u32 v8, s6, v0, v2
	v_mul_u32_u24_e32 v0, 0x90, v6
	v_lshlrev_b32_e32 v2, 1, v7
	s_add_u32 s4, s16, s4
	v_add3_u32 v9, s6, v0, v2
	v_readlane_b32 s6, v227, 13
	s_addc_u32 s5, s17, 0
	s_lshl_b32 s11, s38, 6
	v_readlane_b32 s12, v227, 6
	s_mov_b32 s13, s6
	v_readlane_b32 s42, v229, 6
	v_readlane_b32 s43, v229, 7
	v_readlane_b32 s44, v229, 8
	v_readlane_b32 s45, v229, 9
	v_readlane_b32 s46, v229, 10
	v_readlane_b32 s47, v229, 11
	v_readlane_b32 s48, v229, 12
	v_readlane_b32 s49, v229, 13
	v_readlane_b32 s50, v229, 14
	v_readlane_b32 s51, v229, 15
	v_readlane_b32 s52, v229, 16
	v_readlane_b32 s53, v229, 17
	v_readlane_b32 s54, v229, 18
	v_readlane_b32 s55, v229, 19
	v_readlane_b32 s7, v227, 14
	v_readlane_b32 vcc_lo, v228, 6
	v_readlane_b32 vcc_hi, v228, 7
	v_mov_b32_e32 v242, s13
	v_lshrrev_b32_e32 v242, 9, v242
	v_lshlrev_b32_e32 v244, 15, v242
	v_sub_u32_e32 v244, s12, v244
	v_add_u32_e32 v244, v244, v7
	v_mul_u32_u24_e32 v243, 0xc00, v244
	v_lshl_add_u32 v243, v242, 7, v243
	v_lshl_add_u32 v243, v6, 1, v243
	global_load_dwordx4 v[238:241], v243, vcc
	s_branch .LBB0_270
; DI void phase_hyconv(const Ctx& c) {
;     ...
;     {
;       const int tr = tid >> 3, cs = (tid & 7) * 8;
;       const int tok = t0 + tr, n = tok & (L - 1);
;       float cur[8], prv[8], nxt[8];
;       unpack8(*(const uint4*)(P + (size_t)tok * 1536 + c0 + cs), cur);
;       if (n > 0) unpack8(*(const uint4*)(P + (size_t)(tok - 1) * 1536 + c0 + cs), prv);
;       else { for (int e = 0; e < 8; ++e) prv[e] = 0.f; }
;       if (n < L - 1) unpack8(*(const uint4*)(P + (size_t)(tok + 1) * 1536 + c0 + cs), nxt);
;       else { for (int e = 0; e < 8; ++e) nxt[e] = 0.f; }
; #pragma unroll
;       for (int e = 0; e < 8; ++e) {
;         const int ch = c0 + cs + e;
;         const float v = prv[e] * cw[ch] + cur[e] * cw[1536 + ch] + nxt[e] * cw[3072 + ch] + cb[ch];
;         tileT[(cs + e) * 72 + tr] = f2bf(v);
;       }
;     }
;     __syncthreads();
;     {
;       const int ch = tid >> 3, ts = (tid & 7) * 8;
;       const int cg_ = c0 + ch, part = cg_ >> 9, cc = cg_ & 511;
;       const int seq = t0 >> c.logL, n0 = t0 & (L - 1);
;       bf16* dst = (bf16*)(c.ws + OFF_X1 + (size_t)part * SZ_T512) + ((size_t)(seq * 512 + cc)) * L + n0 + ts;
;       *(uint4*)dst = *(const uint4*)(tileT + ch * 72 + ts);
;     }
;     __syncthreads();
.LBB0_269:
	s_or_b64 exec, exec, s[8:9]
	v_or_b32_e32 v26, s6, v6
	v_ashrrev_i32_e32 v27, 31, v26
	v_lshlrev_b64 v[50:51], 2, v[26:27]
	v_lshl_add_u64 v[46:47], s[0:1], 0, v[50:51]
	s_mov_b64 s[8:9], 0x1800
	s_movk_i32 s7, 0x1000
	v_lshl_add_u64 v[26:27], v[46:47], 0, s[8:9]
	v_add_co_u32_e32 v30, vcc, s7, v46
	global_load_dwordx4 v[26:29], v[26:27], off offset:16
	s_nop 0
	v_addc_co_u32_e32 v31, vcc, 0, v47, vcc
	s_mov_b64 s[8:9], 0x3000
	s_movk_i32 s7, 0x3000
	global_load_dwordx4 v[30:33], v[30:31], off offset:2048
	s_nop 0
	global_load_dwordx4 v[34:37], v[46:47], off offset:16
	global_load_dwordx4 v[38:41], v[46:47], off
	v_lshl_add_u64 v[42:43], v[46:47], 0, s[8:9]
	v_add_co_u32_e32 v46, vcc, s7, v46
	global_load_dwordx4 v[42:45], v[42:43], off offset:16
	s_nop 0
	v_addc_co_u32_e32 v47, vcc, 0, v47, vcc
	global_load_dwordx4 v[46:49], v[46:47], off
	v_lshl_add_u64 v[54:55], s[4:5], 0, v[50:51]
	global_load_dwordx4 v[50:53], v[54:55], off offset:16
	s_nop 0
	global_load_dwordx4 v[54:57], v[54:55], off
	s_add_i32 s7, s12, s14
	s_waitcnt vmcnt(8)
	v_mov_b32_e32 v2, v238
	v_mov_b32_e32 v3, v239
	v_mov_b32_e32 v4, v240
	v_mov_b32_e32 v5, v241
	v_lshlrev_b32_e32 v11, 16, v230
	v_and_b32_e32 v12, 0xffff0000, v230
	v_lshlrev_b32_e32 v13, 16, v231
	v_and_b32_e32 v14, 0xffff0000, v231
	v_lshlrev_b32_e32 v15, 16, v232
	v_and_b32_e32 v16, 0xffff0000, v232
	v_lshlrev_b32_e32 v17, 16, v233
	v_and_b32_e32 v18, 0xffff0000, v233
	v_lshlrev_b32_e32 v10, 16, v234
	v_and_b32_e32 v19, 0xffff0000, v234
	v_lshlrev_b32_e32 v20, 16, v235
	v_and_b32_e32 v21, 0xffff0000, v235
	v_lshlrev_b32_e32 v22, 16, v236
	v_and_b32_e32 v23, 0xffff0000, v236
	v_lshlrev_b32_e32 v24, 16, v237
	v_and_b32_e32 v25, 0xffff0000, v237
	v_lshlrev_b32_e32 v63, 16, v3
	v_and_b32_e32 v64, 0xffff0000, v3
	v_add_u32_e32 v3, s6, v7
	v_lshlrev_b32_e32 v59, 16, v2
	v_and_b32_e32 v62, 0xffff0000, v2
	v_ashrrev_i32_e32 v2, 9, v3
	v_and_b32_e32 v58, 0x1ff, v3
	s_ashr_i32 s6, s7, s87
	s_and_b32 s82, s7, s18
	v_ashrrev_i32_e32 v3, 31, v2
	v_lshl_or_b32 v58, s6, 9, v58
	v_readlane_b32 s6, v228, 10
	v_lshlrev_b32_e32 v65, 16, v4
	v_and_b32_e32 v4, 0xffff0000, v4
	v_lshlrev_b32_e32 v66, 16, v5
	v_and_b32_e32 v5, 0xffff0000, v5
	v_lshlrev_b64 v[2:3], 25, v[2:3]
	v_readlane_b32 s7, v228, 11
	s_add_i32 s13, s13, s38
	s_add_i32 s12, s12, s11
	v_lshl_add_u64 v[60:61], s[6:7], 0, v[2:3]
	s_cmpk_lt_i32 s13, 0x3000
	s_waitcnt vmcnt(7)
	v_mul_f32_e32 v2, v26, v65
	v_mul_f32_e32 v3, v27, v4
	v_mul_f32_e32 v4, v28, v66
	v_mul_f32_e32 v5, v29, v5
	s_waitcnt vmcnt(6)
	v_mul_f32_e32 v26, v30, v59
	v_mul_f32_e32 v27, v31, v62
	v_mul_f32_e32 v28, v32, v63
	v_mul_f32_e32 v29, v33, v64
	s_waitcnt vmcnt(5)
	v_fmac_f32_e32 v2, v15, v34
	v_fmac_f32_e32 v3, v16, v35
	v_fmac_f32_e32 v4, v17, v36
	v_fmac_f32_e32 v5, v18, v37
	s_waitcnt vmcnt(4)
	v_fmac_f32_e32 v26, v11, v38
	v_fmac_f32_e32 v27, v12, v39
	v_fmac_f32_e32 v28, v13, v40
	v_fmac_f32_e32 v29, v14, v41
	s_waitcnt vmcnt(3)
	v_fmac_f32_e32 v2, v22, v42
	v_fmac_f32_e32 v3, v23, v43
	v_fmac_f32_e32 v4, v24, v44
	v_fmac_f32_e32 v5, v25, v45
	s_waitcnt vmcnt(2)
	v_fmac_f32_e32 v26, v10, v46
	v_fmac_f32_e32 v27, v19, v47
	v_fmac_f32_e32 v28, v20, v48
	v_fmac_f32_e32 v29, v21, v49
	s_waitcnt vmcnt(1)
	v_add_f32_e32 v2, v50, v2
	v_add_f32_e32 v3, v51, v3
	v_add_f32_e32 v4, v52, v4
	v_add_f32_e32 v5, v53, v5
	s_waitcnt vmcnt(0)
	v_readlane_b32 vcc_lo, v228, 6
	v_readlane_b32 vcc_hi, v228, 7
	v_mov_b32_e32 v242, s13
	v_lshrrev_b32_e32 v242, 9, v242
	v_lshlrev_b32_e32 v244, 15, v242
	v_sub_u32_e32 v244, s12, v244
	v_add_u32_e32 v244, v244, v7
	v_mul_u32_u24_e32 v243, 0xc00, v244
	v_lshl_add_u32 v243, v242, 7, v243
	v_lshl_add_u32 v243, v6, 1, v243
	global_load_dwordx4 v[238:241], v243, vcc
	v_add_f32_e32 v10, v54, v26
	v_add_f32_e32 v11, v55, v27
	v_add_f32_e32 v12, v56, v28
	v_add_f32_e32 v13, v57, v29
	v_cvt_pk_bf16_f32 v2, v2, s0
	v_cvt_pk_bf16_f32 v3, v3, s0
	v_cvt_pk_bf16_f32 v4, v4, s0
	v_cvt_pk_bf16_f32 v5, v5, s0
	v_cvt_pk_bf16_f32 v10, v10, s0
	v_cvt_pk_bf16_f32 v11, v11, s0
	v_cvt_pk_bf16_f32 v12, v12, s0
	v_cvt_pk_bf16_f32 v13, v13, s0
	ds_write_b16 v9, v2 offset:576
	ds_write_b16 v9, v3 offset:720
	ds_write_b16 v9, v4 offset:864
	ds_write_b16 v9, v5 offset:1008
	ds_write_b16 v9, v10
	ds_write_b16 v9, v11 offset:144
	ds_write_b16 v9, v12 offset:288
	ds_write_b16 v9, v13 offset:432
	s_waitcnt lgkmcnt(0)
	s_barrier
	v_ashrrev_i32_e32 v59, 31, v58
	ds_read_b128 v[2:5], v8
	v_lshlrev_b64 v[10:11], s87, v[58:59]
	v_lshl_add_u64 v[10:11], v[10:11], 1, v[60:61]
	v_lshl_add_u64 v[10:11], s[82:83], 1, v[10:11]
	v_lshl_add_u64 v[10:11], v[10:11], 0, v[0:1]
	s_waitcnt lgkmcnt(0)
	global_store_dwordx4 v[10:11], v[2:5], off
	s_barrier
	s_cbranch_scc0 .LBB0_274
.LBB0_270:
	s_ashr_i32 s6, s13, 31
	s_lshr_b32 s6, s6, 23
	s_add_i32 s6, s13, s6
	s_ashr_i32 s6, s6, 9
	s_lshl_b32 s14, s6, 15
	v_readlane_b32 s8, v228, 6
	s_sub_i32 s7, s12, s14
	v_readlane_b32 s9, v228, 7
	s_lshl_b32 s6, s6, 6
	v_add_u32_e32 v26, s7, v7
	v_mov_b64_e32 v[2:3], s[8:9]
	s_movk_i32 s7, 0xc00
	v_mad_i64_i32 v[2:3], s[8:9], v26, s7, v[2:3]
	s_ashr_i32 s7, s6, 31
	v_lshl_add_u64 v[2:3], s[6:7], 1, v[2:3]
	v_lshlrev_b32_e32 v0, 1, v6
	v_lshl_add_u64 v[2:3], v[2:3], 0, v[0:1]
	v_and_b32_e32 v19, s18, v26
	v_cmp_lt_i32_e32 vcc, 0, v19
	v_mov_b32_e32 v10, 0
	v_mov_b32_e32 v11, 0
	v_mov_b32_e32 v12, 0
	v_mov_b32_e32 v13, 0
	v_mov_b32_e32 v14, 0
	v_mov_b32_e32 v15, 0
	v_mov_b32_e32 v16, 0
	v_mov_b32_e32 v17, 0
	v_mov_b32_e32 v18, 0
	v_mov_b32_e32 v230, 0
	v_mov_b32_e32 v231, 0
	v_mov_b32_e32 v232, 0
	v_mov_b32_e32 v233, 0
	v_mov_b32_e32 v234, 0
	v_mov_b32_e32 v235, 0
	v_mov_b32_e32 v236, 0
	v_mov_b32_e32 v237, 0
	s_and_saveexec_b64 s[8:9], vcc
	s_cbranch_execz .LBB0_272
	v_readlane_b32 s16, v228, 6
	v_readlane_b32 s17, v228, 7
	v_add_u32_e32 v11, -1, v26
	s_movk_i32 s15, 0xc00
	v_mov_b64_e32 v[12:13], s[16:17]
	v_mad_i64_i32 v[12:13], s[16:17], v11, s15, v[12:13]
	v_lshl_add_u64 v[12:13], s[6:7], 1, v[12:13]
	v_lshl_add_u64 v[12:13], v[12:13], 0, v[0:1]
	global_load_dwordx4 v[230:233], v[12:13], off
